# out-projection phases (two units per CU with a bandwidth-bound residual epilogue): every other group of 8 workgroups starts 12 us late so epilogue traffic overlaps the other half's K-loop
# speedup vs baseline: 1.0010x; 1.0010x over previous
.LBB0_1517:
	s_cmp_gt_i32 s40, 6
	s_cselect_b64 s[4:5], -1, 0
	s_cmp_lt_i32 s41, 7
	s_cselect_b64 s[6:7], -1, 0
	s_or_b64 s[4:5], s[4:5], s[6:7]
	s_and_b64 vcc, exec, s[4:5]
	s_cbranch_vccnz .LBB0_1589
	s_and_b32 s99, s2, 8
	s_cmp_eq_u32 s99, 0
	s_cbranch_scc1 .Lstag6_done
	s_sleep 127
	s_sleep 127
	s_sleep 127
.Lstag6_done:
	s_mov_b64 s[4:5], s[0:1]
	s_load_dword s3, s[0:1], 0x230
	v_mbcnt_lo_u32_b32 v0, -1, 0
	v_mbcnt_hi_u32_b32 v8, -1, v0
	s_add_u32 s6, s0, 0x230
	v_add_u32_e32 v0, s63, v8
	s_addc_u32 s7, s1, 0
	s_cmpk_gt_i32 s2, 0x1ff
	v_readfirstlane_b32 s28, v0
	s_cbranch_scc1 .LBB0_1539
	s_ashr_i32 s29, s2, 31
	s_load_dwordx2 s[12:13], s[4:5], 0x1a0
	s_lshr_b32 s8, s29, 29
	s_waitcnt lgkmcnt(0)
	s_add_i32 s20, s2, s8
	s_and_b32 s8, s20, -8
	s_sub_i32 s19, s2, s8
	s_cmp_gt_i32 s19, -1
	s_cbranch_scc0 .LBB0_1521
	s_lshl_b32 s18, s19, 6
	s_mov_b64 s[14:15], 0
	s_branch .LBB0_1522

.LBB0_2186:
	s_cmp_gt_i32 s40, 15
	s_cselect_b64 s[4:5], -1, 0
	s_cmp_lt_i32 s41, 16
	s_cselect_b64 s[6:7], -1, 0
	s_or_b64 s[4:5], s[4:5], s[6:7]
	s_and_b64 vcc, exec, s[4:5]
	s_cbranch_vccnz .LBB0_2265
	s_and_b32 s99, s2, 8
	s_cmp_eq_u32 s99, 0
	s_cbranch_scc1 .Lstag15_done
	s_sleep 127
	s_sleep 127
	s_sleep 127
.Lstag15_done:
	s_mov_b64 s[4:5], s[0:1]
	s_waitcnt lgkmcnt(0)
	s_load_dword s3, s[0:1], 0x230
	s_waitcnt vmcnt(0)
	v_mbcnt_lo_u32_b32 v0, -1, 0
	v_mbcnt_hi_u32_b32 v8, -1, v0
	s_add_u32 s12, s0, 0x230
	v_add_u32_e32 v0, s63, v8
	s_addc_u32 s13, s1, 0
	s_cmpk_gt_i32 s2, 0x1ff
	v_readfirstlane_b32 s30, v0
	s_cbranch_scc1 .LBB0_2215
	s_ashr_i32 s31, s2, 31
	s_load_dwordx2 s[6:7], s[4:5], 0x1e8
	s_load_dwordx2 s[14:15], s[4:5], 0x1b0
	s_lshr_b32 s8, s31, 29
	s_add_i32 s16, s2, s8
	s_and_b32 s8, s16, -8
	s_sub_i32 s11, s2, s8
	s_cmp_gt_i32 s11, -1
	s_cbranch_scc0 .LBB0_2190
	s_lshl_b32 s10, s11, 6
	s_load_dwordx2 s[18:19], s[4:5], 0x158
	s_ashr_i32 s8, s16, 3
	s_cbranch_execz .LBB0_2191
	s_branch .LBB0_2192
